# v45 + same DFT slot spreading (blockIdx & 3) in the last layer's prep phase
# speedup vs baseline: 1.0026x; 1.0026x over previous
; __device__ __forceinline__ int opaque_tid() { int t = threadIdx.x; asm volatile("" : "+v"(t)); return t; }
; __device__ __forceinline__ void phase_prep(const Params& P, int l, unsigned char* lds) {
;     ...
;     for (int item = blockIdx.x; item < ROWS / 64 + NBATCH * 20; item += G) {
;         const int tid = opaque_tid();
;         const int type = item >= ROWS / 64;
;         int r0, b, t0;
;         if (!type) { r0 = item * 64; b = r0 / TT; t0 = r0 - b * TT; }
;         else { const int idx = item - ROWS / 64; b = idx / 20; const int jb = idx - b * 20; t0 = (jb < 4) ? 64 * jb : CTX + 64 * (jb - 4); r0 = b * TT + t0; }
;         const bool is_ctx = t0 < CTX;
.Lprep_last:
	s_and_b32 vcc_lo, s100, 3
	s_cmp_eq_u32 s101, vcc_lo
	s_cbranch_scc1 .Lprep_k0
	s_cmp_gt_u32 s101, vcc_lo
	s_cselect_b32 vcc_hi, 1, 0
	s_sub_u32 s101, s101, vcc_hi
	s_cmp_eq_u32 s101, 2
	s_cbranch_scc1 .Lprep_k3
	s_lshl_b32 s101, s101, 8
	s_add_u32 s101, s101, s100
	s_branch .Lprep_map_done
